# grid-barrier spin loops: poll back-off s_sleep 1 -> s_sleep 0 (faster release detection)
# speedup vs baseline: 1.0013x; 1.0013x over previous
; __global__ void __launch_bounds__(512, 2) fwd_megakernel(Args a) {
;     ...
;     grid.sync();
.LBB0_98:
	s_sleep 0
	global_load_dword v2, v0, s[4:5] offset:32 sc1
	s_waitcnt vmcnt(0)
	v_and_b32_e32 v2, 0xffff0000, v2
	v_cmp_ne_u32_e32 vcc, v2, v1
	s_or_b64 s[6:7], vcc, s[6:7]
	s_andn2_b64 exec, exec, s[6:7]
	s_cbranch_execnz .LBB0_98

; __device__ __forceinline__ unsigned xb_ld(unsigned* p)              { return __hip_atomic_load(p, __ATOMIC_RELAXED, __HIP_MEMORY_SCOPE_AGENT); }
; __device__ __forceinline__ void xcd_barrier_complete(unsigned* bar, unsigned x, unsigned& nloc, unsigned& nx) {
;     const unsigned G = gridDim.x * gridDim.y * gridDim.z;
;     unsigned sum, cnt, mine, sp = 0u;
;     for (;;) {
;         sum = 0u; cnt = 0u; mine = 0u;
; #pragma unroll
;         for (unsigned j = 0; j < 16; ++j) { const unsigned c = xb_ld(&bar[XB_XCNT(j)]); sum += c; cnt += (c > 0u) ? 1u : 0u; mine = (j == x) ? c : mine; }
;         if (sum == G) break;
;         __builtin_amdgcn_s_sleep(1);
;         if ((++sp & 255u) == 0u) { if (xb_ld(&bar[XB_TMO])) break; if (sp > XB_SPIN_CAP) { atomicAdd(&bar[XB_TMO], 1u); break; } }
;     }
;     nloc = mine > 0u ? mine : 1u; nx = cnt > 0u ? cnt : 1u;
; }
.LBB0_139:
	v_readlane_b32 s4, v253, 29
	global_load_dword v11, v195, s[88:89] offset:1024 sc1
	s_waitcnt lgkmcnt(0)
	global_load_dword v0, v195, s[88:89] offset:1280 sc1
	global_load_dword v1, v195, s[88:89] offset:1536 sc1
	global_load_dword v2, v195, s[88:89] offset:1792 sc1
	global_load_dword v3, v195, s[88:89] offset:2048 sc1
	global_load_dword v4, v195, s[88:89] offset:2304 sc1
	global_load_dword v5, v195, s[88:89] offset:2560 sc1
	global_load_dword v6, v195, s[88:89] offset:2816 sc1
	global_load_dword v7, v195, s[88:89] offset:3072 sc1
	global_load_dword v8, v195, s[88:89] offset:3328 sc1
	global_load_dword v9, v195, s[88:89] offset:3584 sc1
	global_load_dword v10, v195, s[88:89] offset:3840 sc1
	v_readlane_b32 s5, v253, 30
	s_mov_b64 s[10:11], -1
	s_mov_b64 s[20:21], -1
	s_waitcnt vmcnt(10)
	v_add_u32_e32 v16, v0, v11
	s_nop 0
	global_load_dword v12, v195, s[4:5] sc1
	v_readlane_b32 s4, v253, 31
	v_readlane_b32 s5, v253, 32
	s_nop 4
	global_load_dword v13, v195, s[4:5] sc1
	global_load_dword v14, v195, s[94:95] sc1
	global_load_dword v15, v195, s[68:69] sc1
	s_waitcnt vmcnt(13)
	v_add_u32_e32 v16, v16, v1
	s_waitcnt vmcnt(12)
	v_add_u32_e32 v16, v16, v2
	s_waitcnt vmcnt(11)
	v_add_u32_e32 v16, v16, v3
	s_waitcnt vmcnt(10)
	v_add_u32_e32 v16, v16, v4
	s_waitcnt vmcnt(9)
	v_add_u32_e32 v16, v16, v5
	s_waitcnt vmcnt(8)
	v_add_u32_e32 v16, v16, v6
	s_waitcnt vmcnt(7)
	v_add_u32_e32 v16, v16, v7
	s_waitcnt vmcnt(6)
	v_add_u32_e32 v16, v16, v8
	s_waitcnt vmcnt(5)
	v_add_u32_e32 v16, v16, v9
	s_waitcnt vmcnt(4)
	v_add_u32_e32 v16, v16, v10
	s_waitcnt vmcnt(3)
	v_add_u32_e32 v16, v16, v12
	s_waitcnt vmcnt(2)
	v_add_u32_e32 v16, v16, v13
	s_waitcnt vmcnt(1)
	v_add_u32_e32 v16, v16, v14
	s_waitcnt vmcnt(0)
	v_add_u32_e32 v16, v16, v15
	v_cmp_eq_u32_e32 vcc, s91, v16
	s_cbranch_vccnz .LBB0_138
	s_and_b32 s7, s6, 0xff
	s_cmp_eq_u32 s7, 0
	s_mov_b64 s[24:25], -1
	s_sleep 0
	s_cbranch_scc1 .LBB0_143
	s_and_b64 vcc, exec, s[24:25]
	s_cbranch_vccz .LBB0_138

.LBB0_157:
	s_and_b32 s7, s6, 0xff
	s_mov_b64 s[38:39], -1
	s_cmp_lg_u32 s7, 0
	s_mov_b64 s[42:43], -1
	s_sleep 0
	s_cbranch_scc0 .LBB0_160
	s_and_b64 vcc, exec, s[42:43]
	s_cbranch_vccz .LBB0_156

; __device__ __forceinline__ unsigned xb_ld(unsigned* p)              { return __hip_atomic_load(p, __ATOMIC_RELAXED, __HIP_MEMORY_SCOPE_AGENT); }
; __device__ __forceinline__ void xcd_barrier_complete(unsigned* bar, unsigned x, unsigned& nloc, unsigned& nx) {
;     const unsigned G = gridDim.x * gridDim.y * gridDim.z;
;     unsigned sum, cnt, mine, sp = 0u;
;     for (;;) {
;         sum = 0u; cnt = 0u; mine = 0u;
; #pragma unroll
;         for (unsigned j = 0; j < 16; ++j) { const unsigned c = xb_ld(&bar[XB_XCNT(j)]); sum += c; cnt += (c > 0u) ? 1u : 0u; mine = (j == x) ? c : mine; }
;         if (sum == G) break;
;         __builtin_amdgcn_s_sleep(1);
;         if ((++sp & 255u) == 0u) { if (xb_ld(&bar[XB_TMO])) break; if (sp > XB_SPIN_CAP) { atomicAdd(&bar[XB_TMO], 1u); break; } }
;     }
;     nloc = mine > 0u ? mine : 1u; nx = cnt > 0u ? cnt : 1u;
; }
.LBB0_304:
	v_readlane_b32 s4, v253, 29
	global_load_dword v11, v195, s[88:89] offset:1024 sc1
	s_waitcnt lgkmcnt(0)
	global_load_dword v0, v195, s[88:89] offset:1280 sc1
	global_load_dword v1, v195, s[88:89] offset:1536 sc1
	global_load_dword v2, v195, s[88:89] offset:1792 sc1
	global_load_dword v3, v195, s[88:89] offset:2048 sc1
	global_load_dword v4, v195, s[88:89] offset:2304 sc1
	global_load_dword v5, v195, s[88:89] offset:2560 sc1
	global_load_dword v6, v195, s[88:89] offset:2816 sc1
	global_load_dword v7, v195, s[88:89] offset:3072 sc1
	global_load_dword v8, v195, s[88:89] offset:3328 sc1
	global_load_dword v9, v195, s[88:89] offset:3584 sc1
	global_load_dword v10, v195, s[88:89] offset:3840 sc1
	v_readlane_b32 s5, v253, 30
	s_mov_b64 s[20:21], -1
	s_mov_b64 s[24:25], -1
	s_waitcnt vmcnt(10)
	v_add_u32_e32 v16, v0, v11
	s_nop 0
	global_load_dword v12, v195, s[4:5] sc1
	v_readlane_b32 s4, v253, 31
	v_readlane_b32 s5, v253, 32
	s_nop 4
	global_load_dword v13, v195, s[4:5] sc1
	global_load_dword v14, v195, s[94:95] sc1
	global_load_dword v15, v195, s[68:69] sc1
	s_waitcnt vmcnt(13)
	v_add_u32_e32 v16, v16, v1
	s_waitcnt vmcnt(12)
	v_add_u32_e32 v16, v16, v2
	s_waitcnt vmcnt(11)
	v_add_u32_e32 v16, v16, v3
	s_waitcnt vmcnt(10)
	v_add_u32_e32 v16, v16, v4
	s_waitcnt vmcnt(9)
	v_add_u32_e32 v16, v16, v5
	s_waitcnt vmcnt(8)
	v_add_u32_e32 v16, v16, v6
	s_waitcnt vmcnt(7)
	v_add_u32_e32 v16, v16, v7
	s_waitcnt vmcnt(6)
	v_add_u32_e32 v16, v16, v8
	s_waitcnt vmcnt(5)
	v_add_u32_e32 v16, v16, v9
	s_waitcnt vmcnt(4)
	v_add_u32_e32 v16, v16, v10
	s_waitcnt vmcnt(3)
	v_add_u32_e32 v16, v16, v12
	s_waitcnt vmcnt(2)
	v_add_u32_e32 v16, v16, v13
	s_waitcnt vmcnt(1)
	v_add_u32_e32 v16, v16, v14
	s_waitcnt vmcnt(0)
	v_add_u32_e32 v16, v16, v15
	v_cmp_eq_u32_e32 vcc, s91, v16
	s_cbranch_vccnz .LBB0_303
	s_and_b32 s4, s6, 0xff
	s_cmp_eq_u32 s4, 0
	s_mov_b64 s[36:37], -1
	s_sleep 0
	s_cbranch_scc1 .LBB0_308
	s_and_b64 vcc, exec, s[36:37]
	s_cbranch_vccz .LBB0_303

.LBB0_322:
	s_and_b32 s4, s6, 0xff
	s_mov_b64 s[40:41], -1
	s_cmp_lg_u32 s4, 0
	s_mov_b64 s[44:45], -1
	s_sleep 0
	s_cbranch_scc0 .LBB0_325
	s_and_b64 vcc, exec, s[44:45]
	s_cbranch_vccz .LBB0_321

; __device__ __forceinline__ unsigned xb_ld(unsigned* p)              { return __hip_atomic_load(p, __ATOMIC_RELAXED, __HIP_MEMORY_SCOPE_AGENT); }
; __device__ __forceinline__ void xcd_barrier_complete(unsigned* bar, unsigned x, unsigned& nloc, unsigned& nx) {
;     const unsigned G = gridDim.x * gridDim.y * gridDim.z;
;     unsigned sum, cnt, mine, sp = 0u;
;     for (;;) {
;         sum = 0u; cnt = 0u; mine = 0u;
; #pragma unroll
;         for (unsigned j = 0; j < 16; ++j) { const unsigned c = xb_ld(&bar[XB_XCNT(j)]); sum += c; cnt += (c > 0u) ? 1u : 0u; mine = (j == x) ? c : mine; }
;         if (sum == G) break;
;         __builtin_amdgcn_s_sleep(1);
;         if ((++sp & 255u) == 0u) { if (xb_ld(&bar[XB_TMO])) break; if (sp > XB_SPIN_CAP) { atomicAdd(&bar[XB_TMO], 1u); break; } }
;     }
;     nloc = mine > 0u ? mine : 1u; nx = cnt > 0u ? cnt : 1u;
; }
.LBB0_387:
	v_readlane_b32 s4, v253, 29
	global_load_dword v11, v195, s[88:89] offset:1024 sc1
	s_waitcnt lgkmcnt(0)
	global_load_dword v0, v195, s[88:89] offset:1280 sc1
	global_load_dword v1, v195, s[88:89] offset:1536 sc1
	global_load_dword v2, v195, s[88:89] offset:1792 sc1
	global_load_dword v3, v195, s[88:89] offset:2048 sc1
	global_load_dword v4, v195, s[88:89] offset:2304 sc1
	global_load_dword v5, v195, s[88:89] offset:2560 sc1
	global_load_dword v6, v195, s[88:89] offset:2816 sc1
	global_load_dword v7, v195, s[88:89] offset:3072 sc1
	global_load_dword v8, v195, s[88:89] offset:3328 sc1
	global_load_dword v9, v195, s[88:89] offset:3584 sc1
	global_load_dword v10, v195, s[88:89] offset:3840 sc1
	v_readlane_b32 s5, v253, 30
	s_mov_b64 s[10:11], -1
	s_mov_b64 s[20:21], -1
	s_waitcnt vmcnt(10)
	v_add_u32_e32 v16, v0, v11
	s_nop 0
	global_load_dword v12, v195, s[4:5] sc1
	v_readlane_b32 s4, v253, 31
	v_readlane_b32 s5, v253, 32
	s_nop 4
	global_load_dword v13, v195, s[4:5] sc1
	global_load_dword v14, v195, s[94:95] sc1
	global_load_dword v15, v195, s[68:69] sc1
	s_waitcnt vmcnt(13)
	v_add_u32_e32 v16, v16, v1
	s_waitcnt vmcnt(12)
	v_add_u32_e32 v16, v16, v2
	s_waitcnt vmcnt(11)
	v_add_u32_e32 v16, v16, v3
	s_waitcnt vmcnt(10)
	v_add_u32_e32 v16, v16, v4
	s_waitcnt vmcnt(9)
	v_add_u32_e32 v16, v16, v5
	s_waitcnt vmcnt(8)
	v_add_u32_e32 v16, v16, v6
	s_waitcnt vmcnt(7)
	v_add_u32_e32 v16, v16, v7
	s_waitcnt vmcnt(6)
	v_add_u32_e32 v16, v16, v8
	s_waitcnt vmcnt(5)
	v_add_u32_e32 v16, v16, v9
	s_waitcnt vmcnt(4)
	v_add_u32_e32 v16, v16, v10
	s_waitcnt vmcnt(3)
	v_add_u32_e32 v16, v16, v12
	s_waitcnt vmcnt(2)
	v_add_u32_e32 v16, v16, v13
	s_waitcnt vmcnt(1)
	v_add_u32_e32 v16, v16, v14
	s_waitcnt vmcnt(0)
	v_add_u32_e32 v16, v16, v15
	v_cmp_eq_u32_e32 vcc, s91, v16
	s_cbranch_vccnz .LBB0_386
	s_and_b32 s4, s6, 0xff
	s_cmp_eq_u32 s4, 0
	s_mov_b64 s[24:25], -1
	s_sleep 0
	s_cbranch_scc1 .LBB0_391
	s_and_b64 vcc, exec, s[24:25]
	s_cbranch_vccz .LBB0_386

.LBB0_405:
	s_and_b32 s4, s6, 0xff
	s_mov_b64 s[38:39], -1
	s_cmp_lg_u32 s4, 0
	s_mov_b64 s[42:43], -1
	s_sleep 0
	s_cbranch_scc0 .LBB0_408
	s_and_b64 vcc, exec, s[42:43]
	s_cbranch_vccz .LBB0_404
